# main GEMM per-tile header: tile_map division by the row-group size (8) as shift/mask, accumulator zeroing interleaved with the scalar decode chain
# baseline (speedup 1.0000x reference)
; __device__ __forceinline__ void gemm_stream(int swave, const GemmJob& J, char* shm, int vb, int G) {
;     ...
; #pragma unroll
;     for (int a_ = 0; a_ < 2; ++a_)
; #pragma unroll
;       for (int b_ = 0; b_ < 2; ++b_)
; #pragma unroll
;         for (int m = 0; m < 4; ++m)
; #pragma unroll
;           for (int n = 0; n < 2; ++n) acc[a_][b_][m][n] = (f32x4){0.f, 0.f, 0.f, 0.f};
.LBB0_726:
	s_add_i32 s19, s19, s67
	s_cmp_ge_i32 s19, s24
	s_cselect_b64 s[6:7], -1, 0
	s_and_b64 vcc, exec, s[6:7]
	s_mov_b32 s28, s5
	s_mov_b32 s56, s4
	s_cbranch_vccnz .Lgz_zero_only
	s_ashr_i32 s10, s19, 31
	v_mov_b64_e32 v[4:5], 0
	s_lshr_b32 s10, s10, 29
	v_mov_b64_e32 v[6:7], 0
	s_add_i32 s10, s19, s10
	v_mov_b64_e32 v[8:9], 0
	s_ashr_i32 s11, s10, 3
	v_mov_b64_e32 v[10:11], 0
	s_and_b32 s10, s10, -8
	v_mov_b64_e32 v[12:13], 0
	s_sub_i32 s10, s19, s10
	v_mov_b64_e32 v[14:15], 0
	s_lshr_b32 s12, s10, 31
	v_mov_b64_e32 v[16:17], 0
	s_or_b32 s12, s12, s25
	v_mov_b64_e32 v[18:19], 0
	s_mul_i32 s10, s12, s10
	v_mov_b64_e32 v[20:21], 0
	s_add_i32 s10, s10, s11
	v_mov_b64_e32 v[22:23], 0
	s_abs_i32 s12, s10
	v_mov_b64_e32 v[24:25], 0
	s_mul_hi_u32 s13, s12, s41
	v_mov_b64_e32 v[26:27], 0
	s_mul_i32 s14, s13, s40
	v_mov_b64_e32 v[28:29], 0
	s_ashr_i32 s11, s10, 31
	v_mov_b64_e32 v[30:31], 0
	s_sub_i32 s12, s12, s14
	v_mov_b64_e32 v[32:33], 0
	s_xor_b32 s11, s11, s35
	v_mov_b64_e32 v[34:35], 0
	s_add_i32 s14, s13, 1
	v_mov_b64_e32 v[36:37], 0
	s_sub_i32 s15, s12, s40
	v_mov_b64_e32 v[38:39], 0
	s_cmp_ge_u32 s12, s40
	v_mov_b64_e32 v[40:41], 0
	s_cselect_b32 s13, s14, s13
	v_mov_b64_e32 v[42:43], 0
	s_cselect_b32 s12, s15, s12
	v_mov_b64_e32 v[44:45], 0
	s_add_i32 s14, s13, 1
	v_mov_b64_e32 v[46:47], 0
	s_cmp_ge_u32 s12, s40
	v_mov_b64_e32 v[48:49], 0
	s_cselect_b32 s12, s14, s13
	v_mov_b64_e32 v[50:51], 0
	s_xor_b32 s12, s12, s11
	v_mov_b64_e32 v[52:53], 0
	s_sub_i32 s11, s12, s11
	v_mov_b64_e32 v[54:55], 0
	s_lshl_b32 s12, s11, 3
	v_mov_b64_e32 v[56:57], 0
	s_mul_i32 s11, s11, s34
	v_mov_b64_e32 v[58:59], 0
	s_sub_i32 s10, s10, s11
	v_mov_b64_e32 v[60:61], 0
	s_lshr_b32 s11, s10, 3
	v_mov_b64_e32 v[62:63], 0
	s_and_b32 s10, s10, 7
	v_mov_b64_e32 v[64:65], 0
	s_add_i32 s10, s10, s12
	v_mov_b64_e32 v[66:67], 0
	s_lshl_b32 s28, s10, 8
	v_mov_b64_e32 v[68:69], 0
	s_ashr_i32 s12, s28, 31
	v_mov_b64_e32 v[70:71], 0
	s_lshl_b32 s56, s11, 8
	v_mov_b64_e32 v[72:73], 0
	s_mul_i32 s10, s12, s38
	v_mov_b64_e32 v[74:75], 0
	s_mul_hi_u32 s11, s28, s38
	v_mov_b64_e32 v[76:77], 0
	s_add_i32 s11, s11, s10
	v_mov_b64_e32 v[78:79], 0
	s_mul_i32 s10, s28, s38
	v_mov_b64_e32 v[80:81], 0
	s_lshl_b64 s[10:11], s[10:11], 1
	v_mov_b64_e32 v[82:83], 0
	v_readlane_b32 s14, v246, 0
	v_readlane_b32 s15, v246, 1
	s_add_u32 s10, s14, s10
	v_mov_b64_e32 v[84:85], 0
	s_mul_i32 s12, s12, s37
	v_mov_b64_e32 v[86:87], 0
	s_mul_hi_u32 s13, s28, s37
	v_mov_b64_e32 v[88:89], 0
	s_addc_u32 s11, s15, s11
	v_mov_b64_e32 v[90:91], 0
	s_add_i32 s13, s13, s12
	v_mov_b64_e32 v[92:93], 0
	s_mul_i32 s12, s28, s37
	v_mov_b64_e32 v[94:95], 0
	s_lshl_b64 s[12:13], s[12:13], 1
	v_mov_b64_e32 v[96:97], 0
	v_readlane_b32 s14, v247, 55
	v_readlane_b32 s15, v247, 56
	s_add_u32 s12, s14, s12
	v_mov_b64_e32 v[98:99], 0
	s_addc_u32 s13, s15, s13
	v_mov_b64_e32 v[100:101], 0
	s_ashr_i32 s14, s56, 31
	v_mov_b64_e32 v[102:103], 0
	s_mul_i32 s14, s14, s76
	v_mov_b64_e32 v[104:105], 0
	s_mul_hi_u32 s15, s56, s76
	v_mov_b64_e32 v[106:107], 0
	s_add_i32 s15, s15, s14
	v_mov_b64_e32 v[108:109], 0
	s_mul_i32 s14, s56, s76
	v_mov_b64_e32 v[110:111], 0
	s_lshl_b64 s[14:15], s[14:15], 1
	v_mov_b64_e32 v[112:113], 0
	v_readlane_b32 s20, v246, 2
	v_readlane_b32 s21, v246, 3
	s_add_u32 s14, s20, s14
	v_mov_b64_e32 v[114:115], 0
	s_addc_u32 s15, s21, s15
	v_mov_b64_e32 v[116:117], 0
	v_mov_b64_e32 v[118:119], 0
	v_mov_b64_e32 v[120:121], 0
	v_mov_b64_e32 v[122:123], 0
	v_mov_b64_e32 v[124:125], 0
	v_mov_b64_e32 v[126:127], 0
	v_mov_b64_e32 v[128:129], 0
	v_mov_b64_e32 v[130:131], 0
	s_branch .LBB0_728
.Lgz_zero_only:
	v_mov_b64_e32 v[4:5], 0
	v_mov_b64_e32 v[6:7], 0
	v_mov_b64_e32 v[8:9], 0
	v_mov_b64_e32 v[10:11], 0
	v_mov_b64_e32 v[12:13], 0
	v_mov_b64_e32 v[14:15], 0
	v_mov_b64_e32 v[16:17], 0
	v_mov_b64_e32 v[18:19], 0
	v_mov_b64_e32 v[20:21], 0
	v_mov_b64_e32 v[22:23], 0
	v_mov_b64_e32 v[24:25], 0
	v_mov_b64_e32 v[26:27], 0
	v_mov_b64_e32 v[28:29], 0
	v_mov_b64_e32 v[30:31], 0
	v_mov_b64_e32 v[32:33], 0
	v_mov_b64_e32 v[34:35], 0
	v_mov_b64_e32 v[36:37], 0
	v_mov_b64_e32 v[38:39], 0
	v_mov_b64_e32 v[40:41], 0
	v_mov_b64_e32 v[42:43], 0
	v_mov_b64_e32 v[44:45], 0
	v_mov_b64_e32 v[46:47], 0
	v_mov_b64_e32 v[48:49], 0
	v_mov_b64_e32 v[50:51], 0
	v_mov_b64_e32 v[52:53], 0
	v_mov_b64_e32 v[54:55], 0
	v_mov_b64_e32 v[56:57], 0
	v_mov_b64_e32 v[58:59], 0
	v_mov_b64_e32 v[60:61], 0
	v_mov_b64_e32 v[62:63], 0
	v_mov_b64_e32 v[64:65], 0
	v_mov_b64_e32 v[66:67], 0
	v_mov_b64_e32 v[68:69], 0
	v_mov_b64_e32 v[70:71], 0
	v_mov_b64_e32 v[72:73], 0
	v_mov_b64_e32 v[74:75], 0
	v_mov_b64_e32 v[76:77], 0
	v_mov_b64_e32 v[78:79], 0
	v_mov_b64_e32 v[80:81], 0
	v_mov_b64_e32 v[82:83], 0
	v_mov_b64_e32 v[84:85], 0
	v_mov_b64_e32 v[86:87], 0
	v_mov_b64_e32 v[88:89], 0
	v_mov_b64_e32 v[90:91], 0
	v_mov_b64_e32 v[92:93], 0
	v_mov_b64_e32 v[94:95], 0
	v_mov_b64_e32 v[96:97], 0
	v_mov_b64_e32 v[98:99], 0
	v_mov_b64_e32 v[100:101], 0
	v_mov_b64_e32 v[102:103], 0
	v_mov_b64_e32 v[104:105], 0
	v_mov_b64_e32 v[106:107], 0
	v_mov_b64_e32 v[108:109], 0
	v_mov_b64_e32 v[110:111], 0
	v_mov_b64_e32 v[112:113], 0
	v_mov_b64_e32 v[114:115], 0
	v_mov_b64_e32 v[116:117], 0
	v_mov_b64_e32 v[118:119], 0
	v_mov_b64_e32 v[120:121], 0
	v_mov_b64_e32 v[122:123], 0
	v_mov_b64_e32 v[124:125], 0
	v_mov_b64_e32 v[126:127], 0
	v_mov_b64_e32 v[128:129], 0
	v_mov_b64_e32 v[130:131], 0
.LBB0_728:
	s_add_u32 s20, s2, 0x100
	s_addc_u32 s21, s3, 0
	s_mov_b32 s2, 0
	s_mov_b32 s29, 2
